# up epilogue reuses first-half shw vectors for prompt units; attention stealing limited to two neighbour queues
# baseline (speedup 1.0000x reference)
; __device__ __forceinline__ int otid(int wv) { (void)wv; int t = threadIdx.x; asm volatile("" : "+v"(t)); return t; }
; __device__ __forceinline__ void attention_phase(const Args& a, int ci, int l, LAS unsigned char* lds, int wv) {
;     ...
;     for (;;) {
;         const int x = (myx + vic) & 7;
;         if (otid(wv) == 0) *qw = atomicAdd(ctr + x, 1u);
;         __syncthreads();
;         const int qi = (int)*qw;
;         __syncthreads();
;         if (qi >= QLEN) { if (++vic >= 8) break; continue; }
.LBB0_1337:
	s_add_i32 s4, s13, 1
	s_cmp_gt_i32 s13, 1
	s_cselect_b64 s[2:3], -1, 0
	s_mov_b32 s13, s4
	s_branch .LBB0_1137

;     __device__ __forceinline__ void operator()(const f32x4 (&acc)[2][2][4][2], const Unit& u, int wr, int wc, int fr, int fq) const {
;     ...
;         for (int ai = 0; ai < 2; ++ai) {
;             const int grp = (u.pm * 256 + ai * 128 + wr * 64) >> 6;
;             float sg[8], sv[8];
;             {
;                 const float* sp = shw + (size_t)batch_of(grp * 64) * 5632 + cn0;
; #pragma unroll
;                 for (int e = 0; e < 8; ++e) { sg[e] = sp[e]; sv[e] = sp[128 + e]; }
;             }
;             float p1[8], p2[8];
; #pragma unroll
;             for (int e = 0; e < 8; ++e) { p1[e] = 0.f; p2[e] = 0.f; }
; #pragma unroll
;             for (int m = 0; m < 4; ++m) {
;                 const int r = EPI_ROW(u, ai, wr, m, fr);
;                 float g[8], v[8], o[8];
; #pragma unroll
;                 for (int e = 0; e < 4; ++e) { g[e] = acc[ai][0][m][0][e]; g[4 + e] = acc[ai][0][m][1][e]; v[e] = acc[ai][1][m][0][e]; v[4 + e] = acc[ai][1][m][1][e]; }
;                 {
;                     const float rstd = rsqrtf(rs[r] * (1.f / 1024.f) + EPS);
; #pragma unroll
;                     for (int e = 0; e < 8; ++e) { g[e] = g[e] * rstd + sg[e]; v[e] = v[e] * rstd + sv[e]; }
;                 }
; #pragma unroll
;                 for (int e = 0; e < 8; ++e) {
;                     const float r1 = __int_as_float(__builtin_amdgcn_update_dpp(0, __float_as_int(g[e]), 0x121, 0xf, 0xf, false));
;                     const float r2 = __int_as_float(__builtin_amdgcn_update_dpp(0, __float_as_int(g[e]), 0x122, 0xf, 0xf, false));
;                     const float gm1 = (fr >= 1) ? r1 : p1[e];
;                     const float gm2 = (fr >= 2) ? r2 : p2[e];
;                     p1[e] = r1; p2[e] = r2;
;                     o[e] = silu_f(w0[e] * gm2 + w1[e] * gm1 + w2[e] * g[e] + bb[e]) * v[e];
;                 }
;                 if (m > 0 || fr >= 2) {
;                     u32x4 w; w.x = cvtpk(o[0], o[1]); w.y = cvtpk(o[2], o[3]); w.z = cvtpk(o[4], o[5]); w.w = cvtpk(o[6], o[7]);
;                     *(u32x4*)(ACT + (size_t)r * FFN + cg0) = w;
;                 } else {
;                     float* f = FIX + ((size_t)grp * 6 + fr) * FFN + cg0;
;                     *(f32x4*)f = (f32x4){g[0], g[1], g[2], g[3]}; *(f32x4*)(f + 4) = (f32x4){g[4], g[5], g[6], g[7]};
;                     float* fv = f + (size_t)2 * FFN;
.LBB0_1700:
	s_or_b64 exec, exec, s[2:3]
	s_add_i32 s5, s36, 0x80
	s_add_i32 s36, s36, 0xffff0080
	s_lshr_b32 s2, s36, 6
	s_ashr_i32 s48, s5, 12
	s_add_i32 s2, s2, 16
	s_cmp_lt_i32 s5, 0x10000
	s_cselect_b32 s2, s48, s2
	s_mul_hi_i32 s3, s2, 0x5800
	s_mulk_i32 s2, 0x5800
	s_add_u32 s2, s88, s2
	v_or_b32_e32 v114, s5, v4
	s_addc_u32 s3, s54, s3
	v_ashrrev_i32_e32 v115, 31, v114
	v_lshl_add_u64 v[110:111], v[194:195], 2, s[2:3]
	v_lshl_add_u64 v[116:117], v[114:115], 2, s[52:53]
	s_cmp_lt_i32 s5, 0x10000
	s_cbranch_scc0 .Lup_shw_ld
	v_mov_b32_e32 v106, v138
	v_mov_b32_e32 v107, v139
	v_mov_b32_e32 v108, v140
	v_mov_b32_e32 v109, v141
	v_mov_b32_e32 v98, v130
	v_mov_b32_e32 v99, v131
	v_mov_b32_e32 v100, v132
	v_mov_b32_e32 v101, v133
	v_mov_b32_e32 v110, v142
	v_mov_b32_e32 v111, v143
	v_mov_b32_e32 v112, v144
	v_mov_b32_e32 v113, v145
	v_mov_b32_e32 v102, v134
	v_mov_b32_e32 v103, v135
	v_mov_b32_e32 v104, v136
	v_mov_b32_e32 v105, v137
	s_branch .Lup_shw_done
.Lup_shw_ld:
	global_load_dwordx4 v[98:101], v[110:111], off offset:16
	global_load_dwordx4 v[106:109], v[110:111], off
	global_load_dwordx4 v[102:105], v[110:111], off offset:528
	s_nop 0
	global_load_dwordx4 v[110:113], v[110:111], off offset:512
	s_waitcnt vmcnt(0)
.Lup_shw_done:
	s_ashr_i32 s26, s5, 6
	s_nop 0
	v_mov_b32_e32 v130, v5
	v_mov_b32_e32 v132, v5
	v_mov_b32_e32 v131, v5
	v_mov_b32_e32 v133, v5
	v_mov_b32_e32 v126, v5
	v_mov_b32_e32 v128, v5
	v_mov_b32_e32 v127, v5
	v_mov_b32_e32 v129, v5
	v_mov_b32_e32 v122, v5
	v_mov_b32_e32 v124, v5
	v_mov_b32_e32 v123, v5
	v_mov_b32_e32 v125, v5
	v_mov_b32_e32 v120, v5
	v_mov_b32_e32 v121, v5
	s_mul_i32 s26, s26, 6
	s_nop 0
	v_mov_b32_e32 v115, v239
	v_fmamk_f32 v115, v115, 0x3a800000, v214
	v_cmp_gt_f32_e32 vcc, s9, v115
	v_mul_f32_e32 v118, 0x4b800000, v115
	s_nop 0
	v_cndmask_b32_e32 v115, v115, v118, vcc
	v_rsq_f32_e32 v115, v115
	s_nop 0
	v_mul_f32_e32 v118, 0x45800000, v115
	v_cndmask_b32_e32 v118, v115, v118, vcc
	v_pk_fma_f32 v[94:95], v[94:95], v[118:119], v[106:107] op_sel_hi:[1,0,1]
	v_pk_fma_f32 v[90:91], v[90:91], v[118:119], v[110:111] op_sel_hi:[1,0,1]
	v_pk_fma_f32 v[96:97], v[96:97], v[118:119], v[108:109] op_sel_hi:[1,0,1]
	v_pk_fma_f32 v[92:93], v[92:93], v[118:119], v[112:113] op_sel_hi:[1,0,1]
	v_pk_fma_f32 v[86:87], v[86:87], v[118:119], v[98:99] op_sel_hi:[1,0,1]
	v_pk_fma_f32 v[82:83], v[82:83], v[118:119], v[102:103] op_sel_hi:[1,0,1]
	v_pk_fma_f32 v[88:89], v[88:89], v[118:119], v[100:101] op_sel_hi:[1,0,1]
	v_pk_fma_f32 v[84:85], v[84:85], v[118:119], v[104:105] op_sel_hi:[1,0,1]
	v_mov_b32_e32 v118, v5
	v_mov_b32_e32 v119, v5
	v_mov_b32_dpp v130, v94 row_ror:1 row_mask:0xf bank_mask:0xf
	v_mov_b32_dpp v132, v94 row_ror:2 row_mask:0xf bank_mask:0xf
	v_mov_b32_dpp v131, v95 row_ror:1 row_mask:0xf bank_mask:0xf
	v_mov_b32_dpp v133, v95 row_ror:2 row_mask:0xf bank_mask:0xf
	v_mov_b32_dpp v126, v96 row_ror:1 row_mask:0xf bank_mask:0xf
	v_mov_b32_dpp v128, v96 row_ror:2 row_mask:0xf bank_mask:0xf
	v_mov_b32_dpp v127, v97 row_ror:1 row_mask:0xf bank_mask:0xf
	v_mov_b32_dpp v129, v97 row_ror:2 row_mask:0xf bank_mask:0xf
	v_mov_b32_dpp v122, v86 row_ror:1 row_mask:0xf bank_mask:0xf
	v_mov_b32_dpp v124, v86 row_ror:2 row_mask:0xf bank_mask:0xf
	v_mov_b32_dpp v123, v87 row_ror:1 row_mask:0xf bank_mask:0xf
	v_mov_b32_dpp v125, v87 row_ror:2 row_mask:0xf bank_mask:0xf
	v_mov_b32_dpp v118, v88 row_ror:1 row_mask:0xf bank_mask:0xf
	v_mov_b32_dpp v120, v88 row_ror:2 row_mask:0xf bank_mask:0xf
	v_mov_b32_dpp v119, v89 row_ror:1 row_mask:0xf bank_mask:0xf
	v_mov_b32_dpp v121, v89 row_ror:2 row_mask:0xf bank_mask:0xf
	s_and_saveexec_b64 s[2:3], s[40:41]
	s_xor_b64 s[2:3], exec, s[2:3]
	s_cbranch_execz .LBB0_1702
	v_readlane_b32 s20, v253, 11
	v_readlane_b32 s21, v253, 12
	v_or_b32_e32 v115, s26, v4
	s_nop 0
	v_mov_b64_e32 v[134:135], s[20:21]
	v_mad_i64_i32 v[134:135], s[20:21], v115, s37, v[134:135]
	v_lshl_add_u64 v[134:135], v[192:193], 2, v[134:135]
	global_store_dwordx4 v[134:135], v[94:97], off
	global_store_dwordx4 v[134:135], v[86:89], off offset:16
	s_nop 1
	v_add_co_u32_e32 v86, vcc, 0x5000, v134
	s_nop 1
	v_addc_co_u32_e32 v87, vcc, 0, v135, vcc
	global_store_dwordx4 v[86:87], v[90:93], off offset:2048
	global_store_dwordx4 v[86:87], v[82:85], off offset:2064
